# phase 0: nt (streaming) hint on the one-shot f32 input / weight loads
# speedup vs baseline: 1.0045x; 1.0045x over previous
; __device__ __forceinline__ float bflo(unsigned u) { return __uint_as_float(u << 16); }
; __device__ __forceinline__ float bfhi(unsigned u) { return __uint_as_float(u & 0xffff0000u); }
; __device__ __forceinline__ void norm_pair_load(NormPair& P, unsigned char* ws, const float* x, const float* ctx, bool first, int l, int which, int sel, int k, int lane) {
;   const float* MODS = (const float*)(ws + WS_MODS); const bf16_t* HB = (const bf16_t*)(ws + WS_HB);
;   const int i = 2 * k;
;   int b, pos; if (sel == 0) { b = i / RB; pos = i - b * RB; } else if (sel == 1) { b = i >> 11; pos = NCTX + (i & 2047); } else { b = i >> 8; pos = i & 255; }
;   const int row = b * RB + pos; P.row = row;
;     ...
;   if (first) { const float* hr = hrow_ptr(ctx, x, row);
; #pragma unroll
;     for (int j = 0; j < 4; ++j) { P.v0[j] = *(const f32x4*)(hr + lane * 4 + 256 * j); P.v1[j] = *(const f32x4*)(hr + DMODEL + lane * 4 + 256 * j); } }
;   else { const bf16_t* hr = HB + (size_t)row * 1024;
; #pragma unroll
;     for (int j = 0; j < 4; ++j) { const u32x2 w = *(const u32x2*)(hr + lane * 4 + 256 * j), w2 = *(const u32x2*)(hr + 1024 + lane * 4 + 256 * j);
;       P.v0[j] = (f32x4){bflo(w.x), bfhi(w.x), bflo(w.y), bfhi(w.y)}; P.v1[j] = (f32x4){bflo(w2.x), bfhi(w2.x), bflo(w2.y), bfhi(w2.y)}; } }
; }
; __device__ __forceinline__ void norm_rows(unsigned char* ws, const float* x, const float* ctx, bool first, int l, int which, int sel, int w0, int wstride, int lane) {
;   const int ppb = (sel == 0 ? RB : sel == 1 ? NLAT : NCTX) >> 1, wpb = wstride >> 4, b = w0 / wpb, wi = w0 - b * wpb, kb = b * ppb, n = (ppb - wi + wpb - 1) / wpb;
;   if (b >= 16 || n <= 0) return;
;   f32x4 sh[4], g[4]; const float* md_cur = nullptr;
;   NormPair A, B; norm_pair_load(A, ws, x, ctx, first, l, which, sel, kb + wi, lane);
;   for (int j = 0; j < n; j += 2) {
;     if (j + 1 < n) norm_pair_load(B, ws, x, ctx, first, l, which, sel, kb + wi + wpb * (j + 1), lane);
;     norm_pair_store(A, sh, g, md_cur, ws, lane);
;     if (j + 1 >= n) break;
;     if (j + 2 < n) norm_pair_load(A, ws, x, ctx, first, l, which, sel, kb + wi + wpb * (j + 2), lane);
;     norm_pair_store(B, sh, g, md_cur, ws, lane);
;   }
; }
.LBB0_251:
	v_mov_b32_e32 v99, 0
	v_lshlrev_b32_e32 v98, 4, v254
	v_lshl_add_u64 v[2:3], s[4:5], 0, v[98:99]
	s_movk_i32 s12, 0x1000
	s_mov_b64 s[8:9], 0x1000
	v_add_co_u32_e32 v26, vcc, s12, v2
	v_lshl_add_u64 v[30:31], v[2:3], 0, s[8:9]
	s_nop 0
	v_addc_co_u32_e32 v27, vcc, 0, v3, vcc
	global_load_dwordx4 v[2:5], v98, s[4:5] nt
	global_load_dwordx4 v[6:9], v98, s[4:5] offset:1024 nt
	global_load_dwordx4 v[10:13], v[30:31], off offset:1024 nt
	global_load_dwordx4 v[14:17], v[30:31], off offset:2048 nt
	global_load_dwordx4 v[18:21], v98, s[4:5] offset:2048 nt
	global_load_dwordx4 v[22:25], v98, s[4:5] offset:3072 nt
	s_nop 0
	global_load_dwordx4 v[26:29], v[26:27], off nt
	s_nop 0
	global_load_dwordx4 v[30:33], v[30:31], off offset:3072 nt
	v_mbcnt_lo_u32_b32 v1, -1, 0
	v_mbcnt_hi_u32_b32 v34, -1, v1
	v_and_b32_e32 v1, 64, v34
	v_add_u32_e32 v35, 64, v1
	v_xor_b32_e32 v1, 1, v34
	v_cmp_lt_i32_e32 vcc, v1, v35
	v_xor_b32_e32 v36, 2, v34
	s_add_u32 s13, s26, 0x100000
	v_cndmask_b32_e32 v1, v34, v1, vcc
	v_cmp_lt_i32_e32 vcc, v36, v35
	s_addc_u32 s29, s27, 0
	s_cmpk_gt_i32 s17, 0xff
	v_cndmask_b32_e32 v36, v34, v36, vcc
	v_lshlrev_b32_e32 v101, 2, v36
	v_xor_b32_e32 v36, 4, v34
	v_cmp_lt_i32_e32 vcc, v36, v35
	s_cselect_b32 s4, s16, 16
	s_mul_hi_i32 s5, s4, 0x6000
	v_cndmask_b32_e32 v36, v34, v36, vcc
	v_lshlrev_b32_e32 v105, 2, v36
	v_xor_b32_e32 v36, 8, v34
	v_cmp_lt_i32_e32 vcc, v36, v35
	s_mulk_i32 s4, 0x6000
	s_add_u32 s16, s13, s4
	v_cndmask_b32_e32 v36, v34, v36, vcc
	v_lshlrev_b32_e32 v106, 2, v36
	v_xor_b32_e32 v36, 16, v34
	v_cmp_lt_i32_e32 vcc, v36, v35
	v_lshlrev_b32_e32 v98, 3, v254
	s_addc_u32 s17, s29, s5
	v_cndmask_b32_e32 v36, v34, v36, vcc
	v_lshlrev_b32_e32 v107, 2, v36
	v_xor_b32_e32 v36, 32, v34
	v_cmp_lt_i32_e32 vcc, v36, v35
	s_mov_b64 s[4:5], 0x9700000
	s_lshl_b32 s35, s39, 1
	v_cndmask_b32_e32 v34, v34, v36, vcc
	v_lshlrev_b32_e32 v108, 2, v34
	v_lshl_add_u64 v[34:35], s[26:27], 0, v[98:99]
	v_lshl_add_u64 v[102:103], v[34:35], 0, s[4:5]
	s_sub_i32 s4, s7, s18
	s_add_i32 s5, s4, 2
	s_mul_i32 s34, s39, s5
	s_mul_i32 s5, s18, 0x480
	s_add_i32 s5, s93, s5
	s_add_i32 s4, s4, 1
	s_add_i32 s5, s5, s3
	s_mul_i32 s3, s7, 0x480
	s_lshl_b32 s38, s39, 2
	s_mul_i32 s39, s39, s4
	s_sub_i32 s3, s5, s3
	s_lshl_b32 s5, s34, 1
	s_mulk_i32 s18, 0x900
	s_lshl_b32 s4, s39, 1
	s_add_i32 s5, s5, s18
	s_lshl_b32 s12, s93, 1
	s_add_i32 s4, s4, s18
	s_add_i32 s5, s5, s12
	s_mulk_i32 s7, 0x900
	s_add_i32 s4, s4, s12
	s_mov_b32 s30, 2
	v_lshlrev_b32_e32 v100, 2, v254
	s_mov_b32 s31, 0
	v_lshlrev_b32_e32 v1, 2, v1
	s_lshl_b32 s36, s92, 4
	s_sub_i32 s37, s5, s7
	s_sub_i32 s40, s4, s7
	s_mov_b64 s[4:5], 0
	s_mov_b32 s12, 0x3a800000
	s_mov_b32 s41, 0x800000
	v_mov_b32_e32 v104, 0x358637bd
	s_branch .LBB0_254

; __device__ __forceinline__ void norm_pair_load(NormPair& P, unsigned char* ws, const float* x, const float* ctx, bool first, int l, int which, int sel, int k, int lane) {
;     ...
;   if (first) { const float* hr = hrow_ptr(ctx, x, row);
; #pragma unroll
;     for (int j = 0; j < 4; ++j) { P.v0[j] = *(const f32x4*)(hr + lane * 4 + 256 * j); P.v1[j] = *(const f32x4*)(hr + DMODEL + lane * 4 + 256 * j); } }
; __device__ __forceinline__ void norm_pair_store(const NormPair& P, f32x4 (&sh)[4], f32x4 (&g)[4], const float*& md_cur, unsigned char* ws, int lane) {
;     ...
; #pragma unroll
.LBB0_259:
	v_lshlrev_b32_e32 v98, 2, v100
	v_lshl_add_u64 v[34:35], s[18:19], 0, v[98:99]
	v_add_co_u32_e32 v58, vcc, 0x1000, v34
	v_lshl_add_u64 v[62:63], v[34:35], 0, s[8:9]
	s_nop 0
	v_addc_co_u32_e32 v59, vcc, 0, v35, vcc
	global_load_dwordx4 v[34:37], v98, s[18:19] nt
	global_load_dwordx4 v[38:41], v98, s[18:19] offset:1024 nt
	global_load_dwordx4 v[46:49], v[62:63], off offset:1024 nt
	global_load_dwordx4 v[54:57], v[62:63], off offset:2048 nt
	global_load_dwordx4 v[42:45], v98, s[18:19] offset:2048 nt
	global_load_dwordx4 v[50:53], v98, s[18:19] offset:3072 nt
	s_nop 0
	global_load_dwordx4 v[58:61], v[58:59], off nt
	s_nop 0
	global_load_dwordx4 v[62:65], v[62:63], off offset:3072 nt
	s_add_i32 s7, s39, s3
	s_mul_hi_i32 s7, s7, 0x38e38e39
	s_lshr_b32 s15, s7, 31
	s_ashr_i32 s7, s7, 8
	s_add_i32 s7, s7, s15
	s_mul_i32 s15, s7, 0xfffff700
	s_add_i32 s15, s14, s15
	s_cmpk_gt_i32 s15, 0xff
	s_cselect_b32 s7, s7, 16
	s_mul_hi_i32 s15, s7, 0x6000
	s_mulk_i32 s7, 0x6000
	s_add_u32 s18, s13, s7
	s_addc_u32 s19, s29, s15
.LBB0_260:
	s_cmp_eq_u64 s[16:17], s[4:5]
	s_cbranch_scc1 .LBB0_262
	v_lshlrev_b32_e32 v98, 2, v100
	v_lshl_add_u64 v[66:67], s[16:17], 0, v[98:99]
	v_add_co_u32_e32 v66, vcc, 0x1000, v66
	s_nop 1
	v_addc_co_u32_e32 v67, vcc, 0, v67, vcc
	global_load_dwordx4 v[82:85], v[66:67], off nt
	global_load_dwordx4 v[86:89], v[66:67], off offset:1024 nt
	global_load_dwordx4 v[90:93], v[66:67], off offset:2048 nt
	global_load_dwordx4 v[70:73], v98, s[16:17] nt
	global_load_dwordx4 v[74:77], v98, s[16:17] offset:1024 nt
	global_load_dwordx4 v[94:97], v[66:67], off offset:3072 nt
	global_load_dwordx4 v[78:81], v98, s[16:17] offset:2048 nt
	s_nop 0
	global_load_dwordx4 v[66:69], v98, s[16:17] offset:3072 nt
	s_waitcnt vmcnt(7)
	v_pk_add_f32 v[84:85], v[84:85], 1.0 op_sel_hi:[1,0]
	v_pk_add_f32 v[82:83], v[82:83], 1.0 op_sel_hi:[1,0]
	s_waitcnt vmcnt(6)
	v_pk_add_f32 v[88:89], v[88:89], 1.0 op_sel_hi:[1,0]
	v_pk_add_f32 v[86:87], v[86:87], 1.0 op_sel_hi:[1,0]
	s_waitcnt vmcnt(5)
	v_pk_add_f32 v[92:93], v[92:93], 1.0 op_sel_hi:[1,0]
	v_pk_add_f32 v[90:91], v[90:91], 1.0 op_sel_hi:[1,0]
	s_waitcnt vmcnt(2)
	v_pk_add_f32 v[96:97], v[96:97], 1.0 op_sel_hi:[1,0]
	v_pk_add_f32 v[94:95], v[94:95], 1.0 op_sel_hi:[1,0]

; __device__ __forceinline__ void norm_pair_load(NormPair& P, unsigned char* ws, const float* x, const float* ctx, bool first, int l, int which, int sel, int k, int lane) {
;     ...
;   if (first) { const float* hr = hrow_ptr(ctx, x, row);
; #pragma unroll
;     for (int j = 0; j < 4; ++j) { P.v0[j] = *(const f32x4*)(hr + lane * 4 + 256 * j); P.v1[j] = *(const f32x4*)(hr + DMODEL + lane * 4 + 256 * j); } }
; __device__ __forceinline__ void norm_pair_store(const NormPair& P, f32x4 (&sh)[4], f32x4 (&g)[4], const float*& md_cur, unsigned char* ws, int lane) {
;     ...
; #pragma unroll
; __device__ __forceinline__ void norm_rows(unsigned char* ws, const float* x, const float* ctx, bool first, int l, int which, int sel, int w0, int wstride, int lane) {
;     ...
;     if (j + 2 < n) norm_pair_load(A, ws, x, ctx, first, l, which, sel, kb + wi + wpb * (j + 2), lane);
.LBB0_268:
	v_lshlrev_b32_e32 v98, 2, v100
	v_lshl_add_u64 v[2:3], s[4:5], 0, v[98:99]
	v_add_co_u32_e32 v26, vcc, 0x1000, v2
	v_lshl_add_u64 v[30:31], v[2:3], 0, s[8:9]
	s_nop 0
	v_addc_co_u32_e32 v27, vcc, 0, v3, vcc
	global_load_dwordx4 v[2:5], v98, s[4:5] nt
	global_load_dwordx4 v[6:9], v98, s[4:5] offset:1024 nt
	global_load_dwordx4 v[10:13], v[30:31], off offset:1024 nt
	global_load_dwordx4 v[14:17], v[30:31], off offset:2048 nt
	global_load_dwordx4 v[18:21], v98, s[4:5] offset:2048 nt
	global_load_dwordx4 v[22:25], v98, s[4:5] offset:3072 nt
	s_nop 0
	global_load_dwordx4 v[26:29], v[26:27], off nt
	s_nop 0
	global_load_dwordx4 v[30:33], v[30:31], off offset:3072 nt
	s_add_i32 s4, s34, s3
	s_mul_hi_i32 s4, s4, 0x38e38e39
	s_lshr_b32 s5, s4, 31
	s_ashr_i32 s4, s4, 8
	s_add_i32 s4, s4, s5
	s_mul_i32 s5, s4, 0xfffff700
	s_add_i32 s5, s6, s5
	s_cmpk_gt_i32 s5, 0xff
	s_cselect_b32 s4, s4, 16
	s_mul_hi_i32 s5, s4, 0x6000
	s_mulk_i32 s4, 0x6000
	s_add_u32 s58, s13, s4
	s_addc_u32 s59, s29, s5
.LBB0_269:
	s_cmp_eq_u64 s[18:19], s[16:17]
	s_cbranch_scc1 .LBB0_252
	v_lshlrev_b32_e32 v98, 2, v100
	v_lshl_add_u64 v[66:67], s[18:19], 0, v[98:99]
	v_add_co_u32_e32 v66, vcc, 0x1000, v66
	s_mov_b64 s[16:17], s[18:19]
	s_nop 0
	v_addc_co_u32_e32 v67, vcc, 0, v67, vcc
	global_load_dwordx4 v[82:85], v[66:67], off nt
	global_load_dwordx4 v[86:89], v[66:67], off offset:1024 nt
	global_load_dwordx4 v[90:93], v[66:67], off offset:2048 nt
	global_load_dwordx4 v[94:97], v[66:67], off offset:3072 nt
	global_load_dwordx4 v[70:73], v98, s[18:19] nt
	global_load_dwordx4 v[74:77], v98, s[18:19] offset:1024 nt
	global_load_dwordx4 v[78:81], v98, s[18:19] offset:2048 nt
	s_nop 0
	global_load_dwordx4 v[66:69], v98, s[18:19] offset:3072 nt
	s_waitcnt vmcnt(7)
	v_pk_add_f32 v[84:85], v[84:85], 1.0 op_sel_hi:[1,0]
	v_pk_add_f32 v[82:83], v[82:83], 1.0 op_sel_hi:[1,0]
	s_waitcnt vmcnt(6)
	v_pk_add_f32 v[88:89], v[88:89], 1.0 op_sel_hi:[1,0]
	v_pk_add_f32 v[86:87], v[86:87], 1.0 op_sel_hi:[1,0]
	s_waitcnt vmcnt(5)
	v_pk_add_f32 v[92:93], v[92:93], 1.0 op_sel_hi:[1,0]
	v_pk_add_f32 v[90:91], v[90:91], 1.0 op_sel_hi:[1,0]
	s_waitcnt vmcnt(4)
	v_pk_add_f32 v[96:97], v[96:97], 1.0 op_sel_hi:[1,0]
	v_pk_add_f32 v[94:95], v[94:95], 1.0 op_sel_hi:[1,0]
	s_branch .LBB0_252

; template <int ph> __device__ __forceinline__ void run_phase(const MArgs& a, unsigned char* lds, int tid, int lane, int wave, int G, int bx, int vcu) {
;     ...
;       if (tid < 128) { const int d = tid >> 6, p = tid & 63, i = (d * 32 + g) * 64 + p;
;         const float lr = a.in[8][i], li = a.in[9][i], dt = expf(a.in[10][d * 32 + g]); const float ar = lr * dt, ai = li * dt;
;         for (int k = 0; k <= 16; ++k) { const float mag = expf(ar * (float)k); float sv, cv; sincosf(ai * (float)k, &sv, &cv); POW[((d * 17 + k) * 64 + p) * 2] = mag * cv; POW[((d * 17 + k) * 64 + p) * 2 + 1] = mag * sv; }
;         const float er = POW[((d * 17 + 1) * 64 + p) * 2], ei = POW[((d * 17 + 1) * 64 + p) * 2 + 1];
;         const float den = lr * lr + li * li, cr = ((er - 1.f) * lr + ei * li) / den, ci = (ei * lr - (er - 1.f) * li) / den;
;         for (int h = 0; h < 16; ++h) { const float br = a.in[11][(size_t)i * 16 + h], bi = a.in[12][(size_t)i * 16 + h];
;           BBc[((d * 64 + p) * 16 + h) * 2] = cr * br - ci * bi; BBc[((d * 64 + p) * 16 + h) * 2 + 1] = cr * bi + ci * br;
;           CCc[((d * 16 + h) * 64 + p) * 2] = a.in[13][((size_t)(d * 32 + g) * 16 + h) * 64 + p]; CCc[((d * 16 + h) * 64 + p) * 2 + 1] = a.in[14][((size_t)(d * 32 + g) * 16 + h) * 64 + p]; }
;         float* LAM = (float*)(ws + WS_S5LAM); LAM[(size_t)i * 2] = POW[((d * 17 + 16) * 64 + p) * 2]; LAM[(size_t)i * 2 + 1] = POW[((d * 17 + 16) * 64 + p) * 2 + 1]; }
.LBB0_283:
	v_lshlrev_b64 v[4:5], 6, v[34:35]
	v_lshl_add_u64 v[26:27], s[76:77], 0, v[4:5]
	v_lshl_add_u64 v[8:9], s[74:75], 0, v[4:5]
	global_load_dwordx4 v[22:25], v[26:27], off nt
	global_load_dwordx4 v[10:13], v[8:9], off nt
	v_lshlrev_b64 v[2:3], 12, v[2:3]
	v_lshl_or_b32 v2, v254, 2, v2
	v_lshl_add_u64 v[38:39], s[78:79], 0, v[2:3]
	global_load_dword v42, v[38:39], off
	v_lshl_add_u64 v[40:41], s[80:81], 0, v[2:3]
	global_load_dword v43, v[40:41], off
	global_load_dwordx4 v[14:17], v[8:9], off offset:16 nt
	global_load_dword v44, v[38:39], off offset:256
	global_load_dword v45, v[40:41], off offset:256
	global_load_dwordx4 v[30:33], v[26:27], off offset:16 nt
	global_load_dword v48, v[38:39], off offset:512
	global_load_dword v49, v[40:41], off offset:512
	v_mul_u32_u24_e32 v4, 0x440, v1
	v_or_b32_e32 v4, v4, v254
	v_pk_mul_f32 v[2:3], v[36:37], v[36:37]
	v_lshlrev_b32_e32 v1, 13, v1
	v_lshl_add_u32 v73, v4, 3, 0
	v_pk_add_f32 v[50:51], v[2:3], v[2:3] op_sel:[0,1] op_sel_hi:[0,1]
	v_add3_u32 v1, 0, v1, v6
	global_load_dwordx4 v[2:5], v[8:9], off offset:48 nt
	global_load_dwordx4 v[18:21], v[8:9], off offset:32 nt
	s_nop 0
	global_load_dwordx4 v[6:9], v[26:27], off offset:48 nt
	s_nop 0
	global_load_dwordx4 v[26:29], v[26:27], off offset:32 nt
	ds_read_b64 v[52:53], v73 offset:512
	global_load_dword v55, v[40:41], off offset:768
	global_load_dword v54, v[38:39], off offset:768
	global_load_dword v56, v[38:39], off offset:1024
	global_load_dword v58, v[38:39], off offset:1280
	global_load_dword v60, v[38:39], off offset:1536
	global_load_dword v62, v[38:39], off offset:1792
	global_load_dword v57, v[40:41], off offset:1024
	global_load_dword v59, v[40:41], off offset:1280
	global_load_dword v61, v[40:41], off offset:1536
	global_load_dword v63, v[40:41], off offset:1792
	global_load_dword v64, v[38:39], off offset:2048
	global_load_dword v66, v[38:39], off offset:2304
	global_load_dword v68, v[38:39], off offset:2560
	global_load_dword v65, v[40:41], off offset:2048
	global_load_dword v67, v[40:41], off offset:2304
	global_load_dword v69, v[40:41], off offset:2560
	v_mov_b32_e32 v46, v37
	v_lshl_add_u32 v72, v0, 7, 0
	s_waitcnt lgkmcnt(0)
	v_add_f32_e32 v52, -1.0, v52
	v_pk_mul_f32 v[46:47], v[46:47], v[52:53] op_sel:[0,1] op_sel_hi:[0,0]
	v_pk_fma_f32 v[70:71], v[36:37], v[52:53], v[46:47]
	v_pk_fma_f32 v[36:37], v[36:37], v[52:53], v[46:47] op_sel_hi:[0,1,1] neg_lo:[0,0,1] neg_hi:[0,0,1]
	v_div_scale_f32 v36, s[0:1], v51, v51, v37
	v_div_scale_f32 v47, s[0:1], v50, v50, v70
	v_rcp_f32_e32 v52, v36
	v_rcp_f32_e32 v53, v47
	v_div_scale_f32 v46, vcc, v37, v51, v37
	v_fma_f32 v74, -v36, v52, 1.0
	v_fma_f32 v75, -v47, v53, 1.0
	v_fmac_f32_e32 v52, v74, v52
	v_div_scale_f32 v71, s[0:1], v70, v50, v70
	v_fmac_f32_e32 v53, v75, v53
	v_mul_f32_e32 v74, v46, v52
	v_mul_f32_e32 v75, v71, v53
	v_fma_f32 v76, -v36, v74, v46
	v_fma_f32 v77, -v47, v75, v71
	v_fmac_f32_e32 v74, v76, v52
	v_fmac_f32_e32 v75, v77, v53
	v_fma_f32 v36, -v36, v74, v46
	v_fma_f32 v46, -v47, v75, v71
	v_div_fmas_f32 v36, v36, v52, v74
	s_mov_b64 vcc, s[0:1]
	v_div_fixup_f32 v37, v36, v51, v37
	v_div_fmas_f32 v36, v46, v53, v75
	v_div_fixup_f32 v36, v36, v50, v70
	s_waitcnt vmcnt(29)
	v_pk_mul_f32 v[46:47], v[22:23], v[36:37] op_sel:[0,1] op_sel_hi:[0,0]
	s_waitcnt vmcnt(28)
	v_pk_fma_f32 v[50:51], v[10:11], v[36:37], v[46:47] neg_lo:[0,0,1] neg_hi:[0,0,1]
	v_pk_fma_f32 v[46:47], v[10:11], v[36:37], v[46:47] op_sel_hi:[0,1,1]
	v_mov_b32_e32 v51, v47
	v_pk_mul_f32 v[22:23], v[36:37], v[22:23] op_sel:[1,1] op_sel_hi:[0,1]
	ds_write_b64 v72, v[50:51] offset:17408
	s_waitcnt vmcnt(26)
	ds_write_b64 v1, v[42:43] offset:33792
	v_mov_b32_e32 v42, v11
	v_pk_fma_f32 v[42:43], v[36:37], v[42:43], v[22:23] neg_lo:[0,0,1] neg_hi:[0,0,1]
	v_pk_fma_f32 v[10:11], v[36:37], v[10:11], v[22:23] op_sel:[0,1,0]
	v_pk_mul_f32 v[22:23], v[36:37], v[24:25] op_sel:[1,0] op_sel_hi:[0,0]
	v_mov_b32_e32 v43, v11
	ds_write_b64 v72, v[42:43] offset:17416
	global_load_dword v10, v[38:39], off offset:2816
	global_load_dword v11, v[40:41], off offset:2816
	v_pk_fma_f32 v[42:43], v[36:37], v[12:13], v[22:23] neg_lo:[0,0,1] neg_hi:[0,0,1]
	v_pk_fma_f32 v[22:23], v[36:37], v[12:13], v[22:23] op_sel_hi:[1,0,1]
	s_waitcnt vmcnt(25)
	ds_write_b64 v1, v[44:45] offset:34304
	v_mov_b32_e32 v43, v23
	v_mov_b32_e32 v12, v25
	global_load_dword v44, v[38:39], off offset:3072
	global_load_dword v45, v[40:41], off offset:3072
	ds_write_b64 v72, v[42:43] offset:17424
	s_waitcnt vmcnt(24)
	ds_write_b64 v1, v[48:49] offset:34816
	v_pk_mul_f32 v[22:23], v[36:37], v[12:13] op_sel:[1,0] op_sel_hi:[0,0]
	v_mov_b32_e32 v12, v13
	v_mov_b32_e32 v42, v13
	v_pk_fma_f32 v[12:13], v[36:37], v[12:13], v[22:23] neg_lo:[0,0,1] neg_hi:[0,0,1]
	v_pk_fma_f32 v[22:23], v[36:37], v[42:43], v[22:23] op_sel_hi:[1,0,1]
	global_load_dword v24, v[38:39], off offset:3328
	global_load_dword v25, v[40:41], off offset:3328
	global_load_dword v42, v[38:39], off offset:3584
	global_load_dword v43, v[40:41], off offset:3584
	v_mov_b32_e32 v13, v23
	ds_write_b64 v72, v[12:13] offset:17432
	s_waitcnt vmcnt(22)
; template <int ph> __device__ __forceinline__ void run_phase(const MArgs& a, unsigned char* lds, int tid, int lane, int wave, int G, int bx, int vcu) {
;     ...
;         for (int h = 0; h < 16; ++h) { const float br = a.in[11][(size_t)i * 16 + h], bi = a.in[12][(size_t)i * 16 + h];
;           BBc[((d * 64 + p) * 16 + h) * 2] = cr * br - ci * bi; BBc[((d * 64 + p) * 16 + h) * 2 + 1] = cr * bi + ci * br;
;           CCc[((d * 16 + h) * 64 + p) * 2] = a.in[13][((size_t)(d * 32 + g) * 16 + h) * 64 + p]; CCc[((d * 16 + h) * 64 + p) * 2 + 1] = a.in[14][((size_t)(d * 32 + g) * 16 + h) * 64 + p]; }
;         float* LAM = (float*)(ws + WS_S5LAM); LAM[(size_t)i * 2] = POW[((d * 17 + 16) * 64 + p) * 2]; LAM[(size_t)i * 2 + 1] = POW[((d * 17 + 16) * 64 + p) * 2 + 1]; }
	ds_write_b64 v1, v[54:55] offset:35328
	v_pk_mul_f32 v[12:13], v[36:37], v[30:31] op_sel:[1,0] op_sel_hi:[0,0]
	v_pk_fma_f32 v[22:23], v[36:37], v[14:15], v[12:13] neg_lo:[0,0,1] neg_hi:[0,0,1]
	v_pk_fma_f32 v[12:13], v[36:37], v[14:15], v[12:13] op_sel_hi:[1,0,1]
	s_nop 0
	v_mov_b32_e32 v23, v13
	global_load_dword v12, v[38:39], off offset:3840
	global_load_dword v13, v[40:41], off offset:3840
	ds_write_b64 v72, v[22:23] offset:17440
	s_waitcnt vmcnt(19)
	ds_write_b64 v1, v[56:57] offset:35840
	v_pk_mul_f32 v[22:23], v[36:37], v[30:31] op_sel:[1,1] op_sel_hi:[0,1]
	v_mov_b32_e32 v30, v15
	v_pk_fma_f32 v[30:31], v[36:37], v[30:31], v[22:23] neg_lo:[0,0,1] neg_hi:[0,0,1]
	v_pk_fma_f32 v[14:15], v[36:37], v[14:15], v[22:23] op_sel:[0,1,0]
	s_nop 0
	v_mov_b32_e32 v31, v15
	v_pk_mul_f32 v[14:15], v[36:37], v[32:33] op_sel:[1,0] op_sel_hi:[0,0]
	v_pk_fma_f32 v[22:23], v[36:37], v[16:17], v[14:15] neg_lo:[0,0,1] neg_hi:[0,0,1]
	v_pk_fma_f32 v[14:15], v[36:37], v[16:17], v[14:15] op_sel_hi:[1,0,1]
	ds_write_b64 v72, v[30:31] offset:17448
	s_waitcnt vmcnt(18)
	ds_write_b64 v1, v[58:59] offset:36352
	v_mov_b32_e32 v23, v15
	v_mov_b32_e32 v14, v33
	ds_write_b64 v72, v[22:23] offset:17456
	s_waitcnt vmcnt(17)
	ds_write_b64 v1, v[60:61] offset:36864
	v_pk_mul_f32 v[14:15], v[36:37], v[14:15] op_sel:[1,0] op_sel_hi:[0,0]
	v_mov_b32_e32 v16, v17
	v_mov_b32_e32 v22, v17
	v_pk_fma_f32 v[16:17], v[36:37], v[16:17], v[14:15] neg_lo:[0,0,1] neg_hi:[0,0,1]
	v_pk_fma_f32 v[14:15], v[36:37], v[22:23], v[14:15] op_sel_hi:[1,0,1]
	s_nop 0
	v_mov_b32_e32 v17, v15
	v_pk_mul_f32 v[14:15], v[36:37], v[26:27] op_sel:[1,0] op_sel_hi:[0,0]
	ds_write_b64 v72, v[16:17] offset:17464
	s_waitcnt vmcnt(16)
	ds_write_b64 v1, v[62:63] offset:37376
	v_pk_fma_f32 v[16:17], v[36:37], v[18:19], v[14:15] neg_lo:[0,0,1] neg_hi:[0,0,1]
	v_pk_fma_f32 v[14:15], v[36:37], v[18:19], v[14:15] op_sel_hi:[1,0,1]
	s_nop 0
	v_mov_b32_e32 v17, v15
	ds_write_b64 v72, v[16:17] offset:17472
	s_waitcnt vmcnt(12)
	ds_write_b64 v1, v[64:65] offset:37888
	v_pk_mul_f32 v[14:15], v[36:37], v[26:27] op_sel:[1,1] op_sel_hi:[0,1]
	v_mov_b32_e32 v16, v19
	v_pk_fma_f32 v[16:17], v[36:37], v[16:17], v[14:15] neg_lo:[0,0,1] neg_hi:[0,0,1]
	v_pk_fma_f32 v[14:15], v[36:37], v[18:19], v[14:15] op_sel:[0,1,0]
	v_mov_b32_e32 v18, v21
	v_mov_b32_e32 v17, v15
	v_pk_mul_f32 v[14:15], v[36:37], v[28:29] op_sel:[1,0] op_sel_hi:[0,0]
	ds_write_b64 v72, v[16:17] offset:17480
	s_waitcnt vmcnt(11)
	ds_write_b64 v1, v[66:67] offset:38400
	v_pk_fma_f32 v[16:17], v[36:37], v[20:21], v[14:15] neg_lo:[0,0,1] neg_hi:[0,0,1]
	v_pk_fma_f32 v[14:15], v[36:37], v[20:21], v[14:15] op_sel_hi:[1,0,1]
	s_nop 0
	v_mov_b32_e32 v17, v15
	v_mov_b32_e32 v14, v29
	ds_write_b64 v72, v[16:17] offset:17488
	s_waitcnt vmcnt(10)
	ds_write_b64 v1, v[68:69] offset:38912
	v_pk_mul_f32 v[14:15], v[36:37], v[14:15] op_sel:[1,0] op_sel_hi:[0,0]
	v_mov_b32_e32 v16, v21
	v_pk_fma_f32 v[16:17], v[36:37], v[16:17], v[14:15] neg_lo:[0,0,1] neg_hi:[0,0,1]
	v_pk_fma_f32 v[14:15], v[36:37], v[18:19], v[14:15] op_sel_hi:[1,0,1]
	s_nop 0
	v_mov_b32_e32 v17, v15
	ds_write_b64 v72, v[16:17] offset:17496
	s_waitcnt vmcnt(8)
	ds_write_b64 v1, v[10:11] offset:39424
	v_pk_mul_f32 v[10:11], v[36:37], v[6:7] op_sel:[1,0] op_sel_hi:[0,0]
	v_pk_fma_f32 v[14:15], v[36:37], v[2:3], v[10:11] neg_lo:[0,0,1] neg_hi:[0,0,1]
	v_pk_fma_f32 v[10:11], v[36:37], v[2:3], v[10:11] op_sel_hi:[1,0,1]
	v_pk_mul_f32 v[6:7], v[36:37], v[6:7] op_sel:[1,1] op_sel_hi:[0,1]
	v_mov_b32_e32 v10, v3
	v_mov_b32_e32 v15, v11
	v_pk_fma_f32 v[10:11], v[36:37], v[10:11], v[6:7] neg_lo:[0,0,1] neg_hi:[0,0,1]
	v_pk_fma_f32 v[2:3], v[36:37], v[2:3], v[6:7] op_sel:[0,1,0]
	ds_write_b64 v72, v[14:15] offset:17504
	s_waitcnt vmcnt(6)
	ds_write_b64 v1, v[44:45] offset:39936
	v_mov_b32_e32 v11, v3
	v_pk_mul_f32 v[2:3], v[36:37], v[8:9] op_sel:[1,0] op_sel_hi:[0,0]
	v_pk_fma_f32 v[6:7], v[36:37], v[4:5], v[2:3] neg_lo:[0,0,1] neg_hi:[0,0,1]
	v_pk_fma_f32 v[2:3], v[36:37], v[4:5], v[2:3] op_sel_hi:[1,0,1]
	ds_write_b64 v72, v[10:11] offset:17512
	s_waitcnt vmcnt(4)
	ds_write_b64 v1, v[24:25] offset:40448
	v_mov_b32_e32 v7, v3
	v_mov_b32_e32 v2, v9
	ds_write_b64 v72, v[6:7] offset:17520
	s_waitcnt vmcnt(2)
	ds_write_b64 v1, v[42:43] offset:40960
	v_pk_mul_f32 v[2:3], v[36:37], v[2:3] op_sel:[1,0] op_sel_hi:[0,0]
	v_mov_b32_e32 v4, v5
	v_mov_b32_e32 v6, v5
	v_pk_fma_f32 v[4:5], v[36:37], v[4:5], v[2:3] neg_lo:[0,0,1] neg_hi:[0,0,1]
	v_pk_fma_f32 v[2:3], v[36:37], v[6:7], v[2:3] op_sel_hi:[1,0,1]
	s_nop 0
	v_mov_b32_e32 v5, v3
	ds_write_b64 v72, v[4:5] offset:17528
	s_waitcnt vmcnt(0)
	ds_write_b64 v1, v[12:13] offset:41472
	ds_read_b64 v[4:5], v73 offset:8192
	v_lshl_add_u64 v[2:3], v[34:35], 3, s[26:27]
	v_add_co_u32_e32 v2, vcc, 0x380000, v2
	s_nop 1
	v_addc_co_u32_e32 v3, vcc, 0, v3, vcc
	s_waitcnt lgkmcnt(0)
	global_store_dwordx2 v[2:3], v[4:5], off
